# grid barrier after the in-projection phases: the third-last arriver of each XCD starts an L2 write-back early (the last 1-2 workgroups run a fourth GEMM unit), so the leader's write-back is short
# baseline (speedup 1.0000x reference)
.Lxb_wait:
	v_add_u32_e32 v0, 2, v6
	v_cmp_eq_u32_e32 vcc, v0, v4
	s_cbranch_vccz .Lxb_poll
	s_mov_b32 s18, 0x20100804
	s_add_i32 s2, s10, -1
	s_lshr_b32 s18, s18, s2
	s_cmp_lt_u32 s2, 32
	s_cselect_b32 s18, s18, 0
	s_bitcmp1_b32 s18, 0
	s_cbranch_scc0 .Lxb_poll
	buffer_wbl2 sc1
